# scan loop v4: gelu of the previous tile runs in the gaps of the C*h MFMA chain (two accumulator sets), address arithmetic between the B*u MFMAs
# speedup vs baseline: 1.0050x; 1.0049x over previous
.LBB0_563:
	s_and_b32 s13, s6, 0xff
	s_lshl_b32 s0, s13, 2
	v_mov_b32_e32 v0, s0
	global_load_dword v2, v0, s[38:39]
	s_lshl_b32 s4, s13, 6
	v_or_b32_e32 v0, s4, v174
	v_lshlrev_b32_e32 v3, 2, v0
	global_load_dword v21, v3, s[58:59]
	global_load_dword v20, v3, s[36:37]
	s_and_b32 s2, s10, 0x1800
	v_or_b32_e32 v1, s2, v182
	v_lshlrev_b32_e32 v1, 3, v1
	s_bfe_u32 s0, s12, 0x70001
	v_and_b32_e32 v1, 0xc180, v1
	v_or_b32_e32 v1, s0, v1
	v_lshlrev_b32_e32 v132, 10, v1
	v_lshl_add_u64 v[150:151], v[144:145], 0, v[132:133]
	v_lshl_add_u64 v[152:153], v[146:147], 0, v[132:133]
	v_lshl_add_u64 v[154:155], v[148:149], 0, v[132:133]
	v_lshlrev_b32_e32 v132, 6, v0
	v_lshl_add_u64 v[0:1], v[136:137], 0, v[132:133]
	global_load_dwordx4 v[4:7], v[0:1], off
	global_load_dwordx4 v[8:11], v[0:1], off offset:16
	v_lshl_add_u64 v[0:1], v[134:135], 0, v[132:133]
	global_load_dwordx4 v[12:15], v[0:1], off
	global_load_dwordx4 v[16:19], v[0:1], off offset:16
	v_or_b32_e32 v0, s4, v173
	v_lshlrev_b32_e32 v22, 2, v0
	v_or_b32_e32 v132, 0x800, v132
	s_bfe_u32 s16, s6, 0x70001
	v_mov_b32_e32 v188, 0
	v_mov_b32_e32 v189, v133
	s_waitcnt vmcnt(6)
	v_mul_f32_e32 v0, 0x3fb8aa3b, v2
	v_exp_f32_e32 v0, v0
	global_load_dword v2, v22, s[58:59]
	global_load_dword v1, v22, s[36:37]
	s_waitcnt vmcnt(7)
	v_mov_b32_e32 v22, v21
	v_mov_b32_e32 v25, v21
	v_mul_f32_e32 v23, v0, v21
	s_waitcnt vmcnt(6)
	v_mul_f32_e32 v24, v0, v20
	v_mul_f32_e32 v23, 0x3fb8aa3b, v23
	v_mul_f32_e32 v24, 0.15915494, v24
	v_exp_f32_e32 v23, v23
	v_sin_f32_e32 v26, v24
	v_cos_f32_e32 v24, v24
	v_mov_b32_e32 v27, v20
	v_mul_f32_e32 v28, v23, v26
	v_fma_f32 v29, v23, v24, -1.0
	v_mov_b32_e32 v24, v28
	v_mov_b32_e32 v26, v29
	v_pk_mul_f32 v[30:31], v[20:21], v[28:29]
	v_pk_mul_f32 v[22:23], v[22:23], v[24:25] op_sel_hi:[0,1]
	v_pk_mul_f32 v[20:21], v[20:21], v[26:27] op_sel_hi:[0,1]
	v_add_f32_e32 v28, v30, v31
	v_add_f32_e32 v21, v23, v21
	v_sub_f32_e32 v22, v22, v20
	v_div_scale_f32 v20, s[0:1], v21, v21, v28
	v_div_scale_f32 v24, s[0:1], v21, v21, v22
	v_rcp_f32_e32 v25, v20
	v_rcp_f32_e32 v26, v24
	v_div_scale_f32 v23, vcc, v28, v21, v28
	v_fma_f32 v29, -v20, v25, 1.0
	v_fma_f32 v30, -v24, v26, 1.0
	v_fmac_f32_e32 v25, v29, v25
	v_div_scale_f32 v27, s[0:1], v22, v21, v22
	v_fmac_f32_e32 v26, v30, v26
	v_mul_f32_e32 v29, v23, v25
	v_mul_f32_e32 v30, v27, v26
	v_fma_f32 v31, -v20, v29, v23
	v_fma_f32 v32, -v24, v30, v27
	v_fmac_f32_e32 v29, v31, v25
	v_fmac_f32_e32 v30, v32, v26
	v_fma_f32 v20, -v20, v29, v23
	v_fma_f32 v23, -v24, v30, v27
	v_div_fmas_f32 v20, v20, v25, v29
	s_mov_b64 vcc, s[0:1]
	v_div_fmas_f32 v23, v23, v26, v30
	v_div_fixup_f32 v22, v23, v21, v22
	v_div_fixup_f32 v20, v20, v21, v28
	s_waitcnt vmcnt(5)
	v_pk_mul_f32 v[24:25], v[4:5], v[22:23] op_sel_hi:[1,0]
	v_pk_mul_f32 v[26:27], v[6:7], v[22:23] op_sel_hi:[1,0]
	s_waitcnt vmcnt(4)
	v_pk_mul_f32 v[28:29], v[8:9], v[22:23] op_sel_hi:[1,0]
	v_pk_mul_f32 v[30:31], v[10:11], v[22:23] op_sel_hi:[1,0]
	s_waitcnt vmcnt(3)
	v_pk_mul_f32 v[32:33], v[12:13], v[22:23] op_sel_hi:[1,0]
	v_pk_mul_f32 v[34:35], v[14:15], v[22:23] op_sel_hi:[1,0]
	s_waitcnt vmcnt(2)
	v_pk_mul_f32 v[36:37], v[16:17], v[22:23] op_sel_hi:[1,0]
	v_pk_mul_f32 v[22:23], v[18:19], v[22:23] op_sel_hi:[1,0]
	v_pk_fma_f32 v[14:15], v[14:15], v[20:21], v[26:27] op_sel_hi:[1,0,1] neg_lo:[0,0,1] neg_hi:[0,0,1]
	v_pk_fma_f32 v[12:13], v[12:13], v[20:21], v[24:25] op_sel_hi:[1,0,1] neg_lo:[0,0,1] neg_hi:[0,0,1]
	v_pk_fma_f32 v[18:19], v[18:19], v[20:21], v[30:31] op_sel_hi:[1,0,1] neg_lo:[0,0,1] neg_hi:[0,0,1]
	v_pk_fma_f32 v[16:17], v[16:17], v[20:21], v[28:29] op_sel_hi:[1,0,1] neg_lo:[0,0,1] neg_hi:[0,0,1]
	v_pk_fma_f32 v[6:7], v[6:7], v[20:21], v[34:35] op_sel_hi:[1,0,1]
	v_pk_fma_f32 v[4:5], v[4:5], v[20:21], v[32:33] op_sel_hi:[1,0,1]
	v_pk_fma_f32 v[10:11], v[10:11], v[20:21], v[22:23] op_sel_hi:[1,0,1]
	v_pk_fma_f32 v[8:9], v[8:9], v[20:21], v[36:37] op_sel_hi:[1,0,1]
	v_cvt_pk_bf16_f32 v104, v12, v13
	v_cvt_pk_bf16_f32 v105, v14, v15
	v_cvt_pk_bf16_f32 v106, v16, v17
	v_cvt_pk_bf16_f32 v107, v18, v19
	v_cvt_pk_bf16_f32 v92, v4, v5
	v_cvt_pk_bf16_f32 v93, v6, v7
	s_nop 0
	v_cvt_pk_bf16_f32 v94, v8, v9
	v_cvt_pk_bf16_f32 v95, v10, v11
	v_lshl_or_b32 v58, s13, 12, v183
	v_mov_b32_e32 v59, 0
	v_lshl_add_u64 v[60:61], v[138:139], 0, v[58:59]
	v_lshl_add_u64 v[62:63], v[140:141], 0, v[58:59]
	global_load_dwordx4 v[196:199], v[60:61], off
	global_load_dwordx4 v[200:203], v[62:63], off
	global_load_dwordx4 v[204:207], v[60:61], off offset:32
	global_load_dwordx4 v[208:211], v[62:63], off offset:32
	global_load_dwordx4 v[212:215], v[60:61], off offset:64
	global_load_dwordx4 v[216:219], v[62:63], off offset:64
	global_load_dwordx4 v[220:223], v[60:61], off offset:96
	global_load_dwordx4 v[224:227], v[62:63], off offset:96
	global_load_dwordx4 v[228:231], v[60:61], off offset:128
	global_load_dwordx4 v[232:235], v[62:63], off offset:128
	global_load_dwordx4 v[236:239], v[60:61], off offset:160
	global_load_dwordx4 v[240:243], v[62:63], off offset:160
	global_load_dwordx4 v[244:247], v[60:61], off offset:192
	global_load_dwordx4 v[40:43], v[62:63], off offset:192
	global_load_dwordx4 v[44:47], v[60:61], off offset:224
	global_load_dwordx4 v[48:51], v[62:63], off offset:224
	global_load_dword v21, v3, s[58:59] offset:128
	global_load_dword v20, v3, s[36:37] offset:128
	v_lshl_add_u64 v[12:13], v[136:137], 0, v[132:133]
	v_lshl_add_u64 v[22:23], v[134:135], 0, v[132:133]
	global_load_dwordx4 v[4:7], v[12:13], off
	global_load_dwordx4 v[8:11], v[12:13], off offset:16
	s_nop 0
	global_load_dwordx4 v[12:15], v[22:23], off
	global_load_dwordx4 v[16:19], v[22:23], off offset:16
	v_lshl_or_b32 v132, s13, 12, v183
	v_lshl_add_u64 v[22:23], v[138:139], 0, v[132:133]
	s_waitcnt vmcnt(7)
	v_mul_f32_e32 v2, v2, v0
	v_mul_f32_e32 v2, 0x3fb8aa3b, v2
	v_exp_f32_e32 v2, v2
	s_waitcnt vmcnt(5)
	v_mul_f32_e32 v3, v0, v21
	s_waitcnt vmcnt(4)
	v_mul_f32_e32 v25, v0, v20
	v_mul_f32_e32 v3, 0x3fb8aa3b, v3
	v_mul_f32_e32 v25, 0.15915494, v25
	v_exp_f32_e32 v3, v3
	v_sin_f32_e32 v26, v25
	v_cos_f32_e32 v25, v25
	v_mov_b32_e32 v24, v21
	v_mov_b32_e32 v27, v21
	v_mul_f32_e32 v30, v3, v26
	v_fma_f32 v31, v3, v25, -1.0
	v_mov_b32_e32 v29, v20
	v_mov_b32_e32 v26, v30
	v_mov_b32_e32 v28, v31
	v_pk_mul_f32 v[32:33], v[20:21], v[30:31]
	v_pk_mul_f32 v[24:25], v[24:25], v[26:27] op_sel_hi:[0,1]
	v_pk_mul_f32 v[20:21], v[20:21], v[28:29] op_sel_hi:[0,1]
	v_add_f32_e32 v3, v32, v33
	v_add_f32_e32 v21, v25, v21
	v_sub_f32_e32 v24, v24, v20
	v_div_scale_f32 v20, s[0:1], v21, v21, v3
	v_div_scale_f32 v26, s[0:1], v21, v21, v24
	v_rcp_f32_e32 v27, v20
	v_rcp_f32_e32 v28, v26
	v_div_scale_f32 v25, vcc, v3, v21, v3
	v_fma_f32 v30, -v20, v27, 1.0
	v_fma_f32 v31, -v26, v28, 1.0
	v_fmac_f32_e32 v27, v30, v27
	v_div_scale_f32 v29, s[0:1], v24, v21, v24
	v_fmac_f32_e32 v28, v31, v28
	v_mul_f32_e32 v30, v25, v27
	v_mul_f32_e32 v31, v29, v28
	v_fma_f32 v32, -v20, v30, v25
	v_fma_f32 v33, -v26, v31, v29
	v_fmac_f32_e32 v30, v32, v27
	v_fmac_f32_e32 v31, v33, v28
	v_fma_f32 v20, -v20, v30, v25
	v_fma_f32 v25, -v26, v31, v29
	v_div_fmas_f32 v20, v20, v27, v30
	s_mov_b64 vcc, s[0:1]
	v_div_fixup_f32 v20, v20, v21, v3
	v_div_fmas_f32 v3, v25, v28, v31
	v_div_fixup_f32 v24, v3, v21, v24
	s_waitcnt vmcnt(3)
	v_pk_mul_f32 v[26:27], v[4:5], v[24:25] op_sel_hi:[1,0]
	v_pk_mul_f32 v[28:29], v[6:7], v[24:25] op_sel_hi:[1,0]
	s_waitcnt vmcnt(2)
	v_pk_mul_f32 v[30:31], v[8:9], v[24:25] op_sel_hi:[1,0]
	v_pk_mul_f32 v[32:33], v[10:11], v[24:25] op_sel_hi:[1,0]
	s_waitcnt vmcnt(1)
	v_pk_mul_f32 v[34:35], v[12:13], v[24:25] op_sel_hi:[1,0]
	v_pk_mul_f32 v[36:37], v[14:15], v[24:25] op_sel_hi:[1,0]
	s_waitcnt vmcnt(0)
	v_pk_mul_f32 v[38:39], v[16:17], v[24:25] op_sel_hi:[1,0]
	v_pk_mul_f32 v[24:25], v[18:19], v[24:25] op_sel_hi:[1,0]
	v_pk_fma_f32 v[12:13], v[12:13], v[20:21], v[26:27] op_sel_hi:[1,0,1] neg_lo:[0,0,1] neg_hi:[0,0,1]
	v_pk_fma_f32 v[6:7], v[6:7], v[20:21], v[36:37] op_sel_hi:[1,0,1]
	v_pk_fma_f32 v[4:5], v[4:5], v[20:21], v[34:35] op_sel_hi:[1,0,1]
	v_pk_fma_f32 v[10:11], v[10:11], v[20:21], v[24:25] op_sel_hi:[1,0,1]
	v_pk_fma_f32 v[8:9], v[8:9], v[20:21], v[38:39] op_sel_hi:[1,0,1]
	v_cvt_pk_bf16_f32 v116, v12, v13
	v_lshl_add_u64 v[12:13], v[140:141], 0, v[132:133]
	v_pk_fma_f32 v[14:15], v[14:15], v[20:21], v[28:29] op_sel_hi:[1,0,1] neg_lo:[0,0,1] neg_hi:[0,0,1]
	v_pk_fma_f32 v[18:19], v[18:19], v[20:21], v[32:33] op_sel_hi:[1,0,1] neg_lo:[0,0,1] neg_hi:[0,0,1]
	v_pk_fma_f32 v[16:17], v[16:17], v[20:21], v[30:31] op_sel_hi:[1,0,1] neg_lo:[0,0,1] neg_hi:[0,0,1]
	v_cvt_pk_bf16_f32 v117, v14, v15
	s_lshl_b32 s1, s6, 3
	v_cvt_pk_bf16_f32 v118, v16, v17
	v_cvt_pk_bf16_f32 v119, v18, v19
	v_cvt_pk_bf16_f32 v112, v4, v5
	v_cvt_pk_bf16_f32 v113, v6, v7
	v_cvt_pk_bf16_f32 v114, v8, v9
	v_cvt_pk_bf16_f32 v115, v10, v11
	s_and_b32 s15, s1, 0x1800
	v_or_b32_e32 v3, s15, v174
	v_lshlrev_b32_e32 v3, 3, v3
	s_lshl_b32 s0, s6, 4
	v_and_b32_e32 v3, 0xc080, v3
	s_and_b32 s14, s0, 16
	v_or_b32_e32 v3, s16, v3
	v_or_b32_e32 v132, s14, v176
	v_lshl_or_b32 v3, v3, 9, v177
	v_or3_b32 v14, s14, v175, v3
	v_or_b32_e32 v3, v3, v132
	v_lshlrev_b32_e32 v3, 1, v3
	v_lshlrev_b32_e32 v14, 1, v14
	v_or_b32_e32 v15, 16, v3
	v_mul_f32_e32 v0, v0, v1
	v_mul_f32_e32 v1, 0.15915494, v0
	v_cos_f32_e32 v0, v1
	v_sin_f32_e32 v1, v1
	s_mov_b64 s[0:1], 0
	s_mov_b32 s16, 0
	v_pk_mul_f32 v[198:199], v[126:127], v[198:199]
	v_pk_mul_f32 v[196:197], v[124:125], v[196:197]
	v_pk_mul_f32 v[202:203], v[130:131], v[202:203]
	v_pk_mul_f32 v[200:201], v[128:129], v[200:201]
	s_nop 0
	v_cvt_pk_bf16_f32 v64, v196, v200
	v_cvt_pk_bf16_f32 v65, v197, v201
	v_cvt_pk_bf16_f32 v66, v198, v202
	v_cvt_pk_bf16_f32 v67, v199, v203
	v_pk_mul_f32 v[206:207], v[126:127], v[206:207]
	v_pk_mul_f32 v[204:205], v[124:125], v[204:205]
	v_pk_mul_f32 v[210:211], v[130:131], v[210:211]
	v_pk_mul_f32 v[208:209], v[128:129], v[208:209]
	s_nop 0
	v_cvt_pk_bf16_f32 v68, v204, v208
	v_cvt_pk_bf16_f32 v69, v205, v209
	v_cvt_pk_bf16_f32 v70, v206, v210
	v_cvt_pk_bf16_f32 v71, v207, v211
	v_pk_mul_f32 v[214:215], v[126:127], v[214:215]
	v_pk_mul_f32 v[212:213], v[124:125], v[212:213]
	v_pk_mul_f32 v[218:219], v[130:131], v[218:219]
	v_pk_mul_f32 v[216:217], v[128:129], v[216:217]
	s_nop 0
	v_cvt_pk_bf16_f32 v72, v212, v216
	v_cvt_pk_bf16_f32 v73, v213, v217
	v_cvt_pk_bf16_f32 v74, v214, v218
	v_cvt_pk_bf16_f32 v75, v215, v219
	v_pk_mul_f32 v[222:223], v[126:127], v[222:223]
	v_pk_mul_f32 v[220:221], v[124:125], v[220:221]
	v_pk_mul_f32 v[226:227], v[130:131], v[226:227]
	v_pk_mul_f32 v[224:225], v[128:129], v[224:225]
	s_nop 0
	v_cvt_pk_bf16_f32 v76, v220, v224
	v_cvt_pk_bf16_f32 v77, v221, v225
	v_cvt_pk_bf16_f32 v78, v222, v226
	v_cvt_pk_bf16_f32 v79, v223, v227
	v_pk_mul_f32 v[230:231], v[126:127], v[230:231]
	v_pk_mul_f32 v[228:229], v[124:125], v[228:229]
	v_pk_mul_f32 v[234:235], v[130:131], v[234:235]
	v_pk_mul_f32 v[232:233], v[128:129], v[232:233]
	s_nop 0
	v_cvt_pk_bf16_f32 v84, v228, v232
	v_cvt_pk_bf16_f32 v85, v229, v233
	v_cvt_pk_bf16_f32 v86, v230, v234
	v_cvt_pk_bf16_f32 v87, v231, v235
	v_pk_mul_f32 v[238:239], v[126:127], v[238:239]
	v_pk_mul_f32 v[236:237], v[124:125], v[236:237]
	v_pk_mul_f32 v[242:243], v[130:131], v[242:243]
	v_pk_mul_f32 v[240:241], v[128:129], v[240:241]
	s_nop 0
	v_cvt_pk_bf16_f32 v88, v236, v240
	v_cvt_pk_bf16_f32 v89, v237, v241
	v_cvt_pk_bf16_f32 v90, v238, v242
	v_cvt_pk_bf16_f32 v91, v239, v243
	v_pk_mul_f32 v[246:247], v[126:127], v[246:247]
	v_pk_mul_f32 v[244:245], v[124:125], v[244:245]
	v_pk_mul_f32 v[42:43], v[130:131], v[42:43]
	v_pk_mul_f32 v[40:41], v[128:129], v[40:41]
	s_nop 0
	v_cvt_pk_bf16_f32 v96, v244, v40
	v_cvt_pk_bf16_f32 v97, v245, v41
	v_cvt_pk_bf16_f32 v98, v246, v42
	v_cvt_pk_bf16_f32 v99, v247, v43
	v_lshl_add_u64 v[12:13], v[142:143], 0, s[4:5]
	s_bfe_u32 s4, s6, 0x10001
	v_pk_mul_f32 v[46:47], v[126:127], v[46:47]
	v_pk_mul_f32 v[44:45], v[124:125], v[44:45]
	v_pk_mul_f32 v[50:51], v[130:131], v[50:51]
	v_pk_mul_f32 v[48:49], v[128:129], v[48:49]
	s_nop 0
	v_cvt_pk_bf16_f32 v108, v44, v48
	v_cvt_pk_bf16_f32 v109, v45, v49
	v_cvt_pk_bf16_f32 v110, v46, v50
	v_cvt_pk_bf16_f32 v111, v47, v51
	global_load_dwordx4 v[100:103], v[12:13], off
	global_load_dwordx4 v[80:83], v[12:13], off offset:32
	global_load_dwordx4 v[120:123], v14, s[54:55]
	global_load_dwordx2 v[158:159], v3, s[54:55]
	global_load_dwordx2 v[156:157], v15, s[54:55]
	v_or_b32_e32 v3, s2, v174
	v_pk_mul_f32 v[160:161], v[0:1], v[2:3] op_sel_hi:[1,0]
	v_lshrrev_b32_e32 v187, 3, v3
	v_pk_mov_b32 v[162:163], v[160:161], v[160:161] op_sel:[1,0]
	v_mov_b32_e32 v164, v160
	v_mov_b32_e32 v165, v160
	v_mov_b32_e32 v166, v161
	v_mov_b32_e32 v167, v161
	v_mov_b32_e32 v184, 0xbdd2d3e8
	global_load_dwordx4 v[168:171], v[152:153], off
	global_load_dwordx2 v[178:179], v[154:155], off
	global_load_dwordx2 v[180:181], v[150:151], off
.Lscan_tile:
	s_cmp_lt_u32 s16, 0x1800
	s_cbranch_scc1 .Lscan_w3_0
	s_waitcnt vmcnt(7)
	s_branch .Lscan_go_0

.Lscan_go_0:
	v_mfma_f32_32x32x16_bf16 v[0:15], v[120:123], v[104:107], 0
	s_and_b32 s18, s16, 0x2000
	s_and_b32 s17, s2, 0x1f00
	s_or_b32 s17, s17, s13
	s_lshl_b32 s17, s17, 12
	s_and_b32 s17, s17, 0x1ffc000
	s_addk_i32 s16, 0x800
	v_mfma_f32_32x32x16_bf16 v[16:31], v[120:123], v[116:119], 0
	v_add_u32_e32 v222, s2, v174
	v_and_or_b32 v223, v187, 14, s4
	v_lshlrev_b32_e32 v225, 5, v222
	v_lshlrev_b32_e32 v226, 1, v222
	v_lshl_or_b32 v227, v223, 9, s18
	v_and_b32_e32 v222, 0x1e0, v225
	v_mfma_f32_32x32x16_bf16 v[32:47], v[120:123], v[92:95], 0
	v_and_b32_e32 v223, 16, v226
	v_or_b32_e32 v224, v222, v132
	v_bitop3_b32 v222, v222, v223, v132 bitop3:0x36
	v_or_b32_e32 v225, s17, v227
	v_bitop3_b32 v226, v224, v223, 8 bitop3:0x36
	v_or_b32_e32 v227, v222, v225
	v_mfma_f32_32x32x16_bf16 v[196:211], v[120:123], v[112:115], 0
	v_lshlrev_b32_e32 v228, 16, v158
	v_and_b32_e32 v229, 0xffff0000, v158
	v_lshlrev_b32_e32 v230, 16, v159
	v_and_b32_e32 v231, 0xffff0000, v159
	v_lshlrev_b32_e32 v232, 16, v156
	v_and_b32_e32 v233, 0xffff0000, v156
	v_lshlrev_b32_e32 v251, 16, v157
	v_and_b32_e32 v252, 0xffff0000, v157
	v_or_b32_e32 v254, v226, v225
	v_lshlrev_b32_e32 v253, 1, v227
	v_lshlrev_b32_e32 v254, 1, v254
	s_add_u32 s0, s0, 0x40000
	s_addc_u32 s1, s1, 0
	v_lshl_add_u64 v[216:217], v[152:153], 0, s[0:1]
	v_lshl_add_u64 v[218:219], v[154:155], 0, s[0:1]
	v_lshl_add_u64 v[220:221], v[150:151], 0, s[0:1]
	global_load_dwordx4 v[120:123], v[216:217], off
	global_load_dwordx2 v[158:159], v[218:219], off
	global_load_dwordx2 v[156:157], v[220:221], off
	v_permlane32_swap_b32_e32 v0, v16
	v_permlane32_swap_b32_e32 v1, v17
	v_permlane32_swap_b32_e32 v2, v18
	v_permlane32_swap_b32_e32 v3, v19
	v_permlane32_swap_b32_e32 v4, v20
	v_permlane32_swap_b32_e32 v5, v21
	v_permlane32_swap_b32_e32 v6, v22
	v_permlane32_swap_b32_e32 v7, v23
	v_permlane32_swap_b32_e32 v8, v24
	v_permlane32_swap_b32_e32 v9, v25
	v_permlane32_swap_b32_e32 v10, v26
	v_permlane32_swap_b32_e32 v11, v27
	v_permlane32_swap_b32_e32 v12, v28
	v_permlane32_swap_b32_e32 v13, v29
	v_permlane32_swap_b32_e32 v14, v30
	v_permlane32_swap_b32_e32 v15, v31
	v_permlane32_swap_b32_e32 v32, v196
	v_permlane32_swap_b32_e32 v33, v197
	v_permlane32_swap_b32_e32 v34, v198
	v_permlane32_swap_b32_e32 v35, v199
	v_permlane32_swap_b32_e32 v36, v200
	v_permlane32_swap_b32_e32 v37, v201
	v_permlane32_swap_b32_e32 v38, v202
	v_permlane32_swap_b32_e32 v39, v203
	v_permlane32_swap_b32_e32 v40, v204
	v_permlane32_swap_b32_e32 v41, v205
	v_permlane32_swap_b32_e32 v42, v206
	v_permlane32_swap_b32_e32 v43, v207
	v_permlane32_swap_b32_e32 v44, v208
	v_permlane32_swap_b32_e32 v45, v209
	v_permlane32_swap_b32_e32 v46, v210
	v_permlane32_swap_b32_e32 v47, v211
	v_fmac_f32_e32 v0, v160, v188
	v_fmac_f32_e32 v32, v160, v189
	v_fma_f32 v0, -v161, v189, v0
	v_fmac_f32_e32 v32, v161, v188
	v_fmac_f32_e32 v1, v160, v0
	v_fmac_f32_e32 v33, v160, v32
	v_cvt_pk_bf16_f32 v212, v0, v32
	v_fma_f32 v1, -v161, v32, v1
	v_fmac_f32_e32 v33, v161, v0
	ds_write_b32 v185, v212 offset:18432
	v_fmac_f32_e32 v2, v160, v1
	v_fmac_f32_e32 v34, v160, v33
	v_cvt_pk_bf16_f32 v213, v1, v33
	v_fma_f32 v2, -v161, v33, v2
	v_fmac_f32_e32 v34, v161, v1
	ds_write_b32 v185, v213 offset:18704
	v_fmac_f32_e32 v3, v160, v2
	v_fmac_f32_e32 v35, v160, v34
	v_cvt_pk_bf16_f32 v214, v2, v34
	v_fma_f32 v3, -v161, v34, v3
	v_fmac_f32_e32 v35, v161, v2
	ds_write_b32 v185, v214 offset:18976
	v_fmac_f32_e32 v16, v160, v3
	v_fmac_f32_e32 v196, v160, v35
	v_cvt_pk_bf16_f32 v215, v3, v35
	v_fma_f32 v16, -v161, v35, v16
	v_fmac_f32_e32 v196, v161, v3
	ds_write_b32 v185, v215 offset:19248
	v_fmac_f32_e32 v17, v160, v16
	v_fmac_f32_e32 v197, v160, v196
	v_cvt_pk_bf16_f32 v212, v16, v196
	v_fma_f32 v17, -v161, v196, v17
	v_fmac_f32_e32 v197, v161, v16
	ds_write_b32 v185, v212 offset:19520
	v_fmac_f32_e32 v18, v160, v17
	v_fmac_f32_e32 v198, v160, v197
	v_cvt_pk_bf16_f32 v213, v17, v197
	v_fma_f32 v18, -v161, v197, v18
	v_fmac_f32_e32 v198, v161, v17
	ds_write_b32 v185, v213 offset:19792
	v_fmac_f32_e32 v19, v160, v18
	v_fmac_f32_e32 v199, v160, v198
	v_cvt_pk_bf16_f32 v214, v18, v198
	v_fma_f32 v19, -v161, v198, v19
	v_fmac_f32_e32 v199, v161, v18
	ds_write_b32 v185, v214 offset:20064
	v_fmac_f32_e32 v4, v160, v19
	v_fmac_f32_e32 v36, v160, v199
	v_cvt_pk_bf16_f32 v215, v19, v199
	v_fma_f32 v4, -v161, v199, v4
	v_fmac_f32_e32 v36, v161, v19
	ds_write_b32 v185, v215 offset:20336
	v_fmac_f32_e32 v5, v160, v4
	v_fmac_f32_e32 v37, v160, v36
	v_cvt_pk_bf16_f32 v212, v4, v36
	v_fma_f32 v5, -v161, v36, v5
	v_fmac_f32_e32 v37, v161, v4
	ds_write_b32 v185, v212 offset:20608
	v_fmac_f32_e32 v6, v160, v5
	v_fmac_f32_e32 v38, v160, v37
	v_cvt_pk_bf16_f32 v213, v5, v37
	v_fma_f32 v6, -v161, v37, v6
	v_fmac_f32_e32 v38, v161, v5
	ds_write_b32 v185, v213 offset:20880
	v_fmac_f32_e32 v7, v160, v6
	v_fmac_f32_e32 v39, v160, v38
	v_cvt_pk_bf16_f32 v214, v6, v38
	v_fma_f32 v7, -v161, v38, v7
	v_fmac_f32_e32 v39, v161, v6
	ds_write_b32 v185, v214 offset:21152
	v_fmac_f32_e32 v20, v160, v7
	v_fmac_f32_e32 v200, v160, v39
	v_cvt_pk_bf16_f32 v215, v7, v39
	v_fma_f32 v20, -v161, v39, v20
	v_fmac_f32_e32 v200, v161, v7
	ds_write_b32 v185, v215 offset:21424
	v_fmac_f32_e32 v21, v160, v20
	v_fmac_f32_e32 v201, v160, v200
	v_cvt_pk_bf16_f32 v212, v20, v200
	v_fma_f32 v21, -v161, v200, v21
	v_fmac_f32_e32 v201, v161, v20
	ds_write_b32 v185, v212 offset:21696
	v_fmac_f32_e32 v22, v160, v21
	v_fmac_f32_e32 v202, v160, v201
	v_cvt_pk_bf16_f32 v213, v21, v201
	v_fma_f32 v22, -v161, v201, v22
	v_fmac_f32_e32 v202, v161, v21
	ds_write_b32 v185, v213 offset:21968
	v_fmac_f32_e32 v23, v160, v22
	v_fmac_f32_e32 v203, v160, v202
	v_cvt_pk_bf16_f32 v214, v22, v202
	v_fma_f32 v23, -v161, v202, v23
	v_fmac_f32_e32 v203, v161, v22
	ds_write_b32 v185, v214 offset:22240
	v_fmac_f32_e32 v8, v160, v23
	v_fmac_f32_e32 v40, v160, v203
	v_cvt_pk_bf16_f32 v215, v23, v203
	v_fma_f32 v8, -v161, v203, v8
	v_fmac_f32_e32 v40, v161, v23
	ds_write_b32 v185, v215 offset:22512
	v_fmac_f32_e32 v9, v160, v8
	v_fmac_f32_e32 v41, v160, v40
	v_cvt_pk_bf16_f32 v212, v8, v40
	v_fma_f32 v9, -v161, v40, v9
	v_fmac_f32_e32 v41, v161, v8
	ds_write_b32 v185, v212 offset:22784
	v_fmac_f32_e32 v10, v160, v9
	v_fmac_f32_e32 v42, v160, v41
	v_cvt_pk_bf16_f32 v213, v9, v41
	v_fma_f32 v10, -v161, v41, v10
	v_fmac_f32_e32 v42, v161, v9
	ds_write_b32 v185, v213 offset:23056
	v_fmac_f32_e32 v11, v160, v10
	v_fmac_f32_e32 v43, v160, v42
	v_cvt_pk_bf16_f32 v214, v10, v42
	v_fma_f32 v11, -v161, v42, v11
	v_fmac_f32_e32 v43, v161, v10
	ds_write_b32 v185, v214 offset:23328
	v_fmac_f32_e32 v24, v160, v11
	v_fmac_f32_e32 v204, v160, v43
	v_cvt_pk_bf16_f32 v215, v11, v43
	v_fma_f32 v24, -v161, v43, v24
	v_fmac_f32_e32 v204, v161, v11
	ds_write_b32 v185, v215 offset:23600
	v_fmac_f32_e32 v25, v160, v24
	v_fmac_f32_e32 v205, v160, v204
	v_cvt_pk_bf16_f32 v212, v24, v204
	v_fma_f32 v25, -v161, v204, v25
	v_fmac_f32_e32 v205, v161, v24
	ds_write_b32 v185, v212 offset:23872
	v_fmac_f32_e32 v26, v160, v25
	v_fmac_f32_e32 v206, v160, v205
	v_cvt_pk_bf16_f32 v213, v25, v205
	v_fma_f32 v26, -v161, v205, v26
	v_fmac_f32_e32 v206, v161, v25
	ds_write_b32 v185, v213 offset:24144
	v_fmac_f32_e32 v27, v160, v26
	v_fmac_f32_e32 v207, v160, v206
	v_cvt_pk_bf16_f32 v214, v26, v206
	v_fma_f32 v27, -v161, v206, v27
	v_fmac_f32_e32 v207, v161, v26
	ds_write_b32 v185, v214 offset:24416
	v_fmac_f32_e32 v12, v160, v27
	v_fmac_f32_e32 v44, v160, v207
	v_cvt_pk_bf16_f32 v215, v27, v207
	v_fma_f32 v12, -v161, v207, v12
	v_fmac_f32_e32 v44, v161, v27
	ds_write_b32 v185, v215 offset:24688
	v_fmac_f32_e32 v13, v160, v12
	v_fmac_f32_e32 v45, v160, v44
	v_cvt_pk_bf16_f32 v212, v12, v44
	v_fma_f32 v13, -v161, v44, v13
	v_fmac_f32_e32 v45, v161, v12
	ds_write_b32 v185, v212 offset:24960
	v_fmac_f32_e32 v14, v160, v13
	v_fmac_f32_e32 v46, v160, v45
	v_cvt_pk_bf16_f32 v213, v13, v45
	v_fma_f32 v14, -v161, v45, v14
	v_fmac_f32_e32 v46, v161, v13
	ds_write_b32 v185, v213 offset:25232
	v_fmac_f32_e32 v15, v160, v14
	v_fmac_f32_e32 v47, v160, v46
	v_cvt_pk_bf16_f32 v214, v14, v46
	v_fma_f32 v15, -v161, v46, v15
	v_fmac_f32_e32 v47, v161, v14
	ds_write_b32 v185, v214 offset:25504
	v_fmac_f32_e32 v28, v160, v15
	v_fmac_f32_e32 v208, v160, v47
	v_cvt_pk_bf16_f32 v215, v15, v47
	v_fma_f32 v28, -v161, v47, v28
	v_fmac_f32_e32 v208, v161, v15
	ds_write_b32 v185, v215 offset:25776
	v_fmac_f32_e32 v29, v160, v28
	v_fmac_f32_e32 v209, v160, v208
	v_cvt_pk_bf16_f32 v212, v28, v208
	v_fma_f32 v29, -v161, v208, v29
	v_fmac_f32_e32 v209, v161, v28
	ds_write_b32 v185, v212 offset:26048
	v_fmac_f32_e32 v30, v160, v29
	v_fmac_f32_e32 v210, v160, v209
	v_cvt_pk_bf16_f32 v213, v29, v209
	v_fma_f32 v30, -v161, v209, v30
	v_fmac_f32_e32 v210, v161, v29
	ds_write_b32 v185, v213 offset:26320
	v_fmac_f32_e32 v31, v160, v30
	v_fmac_f32_e32 v211, v160, v210
	v_cvt_pk_bf16_f32 v214, v30, v210
	v_fma_f32 v31, -v161, v210, v31
	v_fmac_f32_e32 v211, v161, v30
	ds_write_b32 v185, v214 offset:26592
	v_mov_b32_e32 v188, v31
	v_mov_b32_e32 v189, v211
	v_cvt_pk_bf16_f32 v215, v31, v211
	ds_write_b32 v185, v215 offset:26864
	s_waitcnt lgkmcnt(0)
	ds_read_b128 v[32:35], v186 offset:18432
	ds_read_b128 v[36:39], v186 offset:18464
	ds_read_b128 v[40:43], v186 offset:18496
	ds_read_b128 v[44:47], v186 offset:18528
	ds_read_b128 v[196:199], v186 offset:18560
	ds_read_b128 v[200:203], v186 offset:18592
	ds_read_b128 v[204:207], v186 offset:18624
	ds_read_b128 v[208:211], v186 offset:18656
	s_waitcnt lgkmcnt(7)
	v_mfma_f32_32x32x16_bf16 v[48:63], v[64:67], v[32:35], 0
	v_fmac_f32_e32 v234, v100, v162
	v_fmac_f32_e32 v235, v101, v163
	v_fmac_f32_e32 v236, v102, v164
	v_fmac_f32_e32 v237, v103, v165
	v_fmac_f32_e32 v238, v80, v166
	v_fmac_f32_e32 v239, v81, v167
	v_fmac_f32_e32 v240, v82, v192
	v_fmac_f32_e32 v241, v83, v193
	v_mul_f32_e32 v242, v234, v234
	s_waitcnt lgkmcnt(6)
	v_mfma_f32_32x32x16_bf16 v[48:63], v[68:71], v[36:39], v[48:63]
	v_mul_f32_e32 v243, v235, v235
	v_mul_f32_e32 v244, v236, v236
	v_mul_f32_e32 v245, v237, v237
	v_mul_f32_e32 v246, v238, v238
	v_mul_f32_e32 v247, v239, v239
	v_mul_f32_e32 v248, v240, v240
	v_mul_f32_e32 v249, v241, v241
	v_fmaak_f32 v242, v242, v184, 0xc0135761
	v_fmaak_f32 v243, v243, v184, 0xc0135761
	s_waitcnt lgkmcnt(5)
	v_mfma_f32_32x32x16_bf16 v[48:63], v[72:75], v[40:43], v[48:63]
	v_fmaak_f32 v244, v244, v184, 0xc0135761
	v_fmaak_f32 v245, v245, v184, 0xc0135761
	v_fmaak_f32 v246, v246, v184, 0xc0135761
	v_fmaak_f32 v247, v247, v184, 0xc0135761
	v_fmaak_f32 v248, v248, v184, 0xc0135761
	v_fmaak_f32 v249, v249, v184, 0xc0135761
	v_mul_f32_e32 v242, v234, v242
	v_mul_f32_e32 v243, v235, v243
	v_mul_f32_e32 v244, v236, v244
	s_waitcnt lgkmcnt(4)
	v_mfma_f32_32x32x16_bf16 v[48:63], v[76:79], v[44:47], v[48:63]
	v_mul_f32_e32 v245, v237, v245
	v_mul_f32_e32 v246, v238, v246
	v_mul_f32_e32 v247, v239, v247
	v_mul_f32_e32 v248, v240, v248
	v_mul_f32_e32 v249, v241, v249
	v_exp_f32_e32 v242, v242
	v_exp_f32_e32 v243, v243
	v_exp_f32_e32 v244, v244
	v_exp_f32_e32 v245, v245
	s_waitcnt lgkmcnt(3)
	v_mfma_f32_32x32x16_bf16 v[48:63], v[84:87], v[196:199], v[48:63]
	v_exp_f32_e32 v246, v246
	v_exp_f32_e32 v247, v247
	v_exp_f32_e32 v248, v248
	v_exp_f32_e32 v249, v249
	v_add_f32_e32 v242, 1.0, v242
	v_add_f32_e32 v243, 1.0, v243
	v_add_f32_e32 v244, 1.0, v244
	v_add_f32_e32 v245, 1.0, v245
	s_waitcnt lgkmcnt(2)
	v_mfma_f32_32x32x16_bf16 v[48:63], v[88:91], v[200:203], v[48:63]
	v_add_f32_e32 v246, 1.0, v246
	v_add_f32_e32 v247, 1.0, v247
	v_add_f32_e32 v248, 1.0, v248
	v_add_f32_e32 v249, 1.0, v249
	v_rcp_f32_e32 v242, v242
	v_rcp_f32_e32 v243, v243
	v_rcp_f32_e32 v244, v244
	v_rcp_f32_e32 v245, v245
	s_waitcnt lgkmcnt(1)
	v_mfma_f32_32x32x16_bf16 v[48:63], v[96:99], v[204:207], v[48:63]
	v_rcp_f32_e32 v246, v246
	v_rcp_f32_e32 v247, v247
	v_rcp_f32_e32 v248, v248
	v_rcp_f32_e32 v249, v249
	v_mul_f32_e32 v234, v234, v242
	v_mul_f32_e32 v235, v235, v243
	v_mul_f32_e32 v236, v236, v244
	v_mul_f32_e32 v237, v237, v245
	s_waitcnt lgkmcnt(0)
	v_mfma_f32_32x32x16_bf16 v[48:63], v[108:111], v[208:211], v[48:63]
	v_mul_f32_e32 v238, v238, v246
	v_mul_f32_e32 v239, v239, v247
	v_mul_f32_e32 v240, v240, v248
	v_mul_f32_e32 v241, v241, v249
	v_cvt_pk_bf16_f32 v242, v234, v235
	v_cvt_pk_bf16_f32 v243, v236, v237
	v_cvt_pk_bf16_f32 v244, v238, v239
	v_cvt_pk_bf16_f32 v245, v240, v241
	s_cmp_eq_u32 s16, 0x800
	s_cbranch_scc1 .Lscan_nostore
	global_store_dwordx2 v190, v[242:243], s[90:91]
	global_store_dwordx2 v191, v[244:245], s[90:91]
.Lscan_nostore:
	s_add_i32 s2, s2, 32
	v_add_u32_e32 v187, 4, v187
	s_cmp_lt_u32 s16, 0x1800
	s_cbranch_scc1 .Lscan_w3_1
	s_waitcnt vmcnt(7)
	s_branch .Lscan_go_1

.Lscan_go_1:
	v_mfma_f32_32x32x16_bf16 v[0:15], v[168:171], v[104:107], 0
	s_and_b32 s18, s16, 0x2000
	s_and_b32 s17, s2, 0x1f00
	s_or_b32 s17, s17, s13
	s_lshl_b32 s17, s17, 12
	s_and_b32 s17, s17, 0x1ffc000
	s_addk_i32 s16, 0x800
	v_mfma_f32_32x32x16_bf16 v[16:31], v[168:171], v[116:119], 0
	v_add_u32_e32 v222, s2, v174
	v_and_or_b32 v223, v187, 14, s4
	v_lshlrev_b32_e32 v225, 5, v222
	v_lshlrev_b32_e32 v226, 1, v222
	v_lshl_or_b32 v227, v223, 9, s18
	v_and_b32_e32 v222, 0x1e0, v225
	v_mfma_f32_32x32x16_bf16 v[32:47], v[168:171], v[92:95], 0
	v_and_b32_e32 v223, 16, v226
	v_or_b32_e32 v224, v222, v132
	v_bitop3_b32 v222, v222, v223, v132 bitop3:0x36
	v_or_b32_e32 v225, s17, v227
	v_bitop3_b32 v226, v224, v223, 8 bitop3:0x36
	v_or_b32_e32 v227, v222, v225
	v_mfma_f32_32x32x16_bf16 v[196:211], v[168:171], v[112:115], 0
	v_lshlrev_b32_e32 v162, 16, v178
	v_and_b32_e32 v163, 0xffff0000, v178
	v_lshlrev_b32_e32 v164, 16, v179
	v_and_b32_e32 v165, 0xffff0000, v179
	v_lshlrev_b32_e32 v166, 16, v180
	v_and_b32_e32 v167, 0xffff0000, v180
	v_lshlrev_b32_e32 v192, 16, v181
	v_and_b32_e32 v193, 0xffff0000, v181
	v_or_b32_e32 v191, v226, v225
	v_lshlrev_b32_e32 v190, 1, v227
	v_lshlrev_b32_e32 v191, 1, v191
	s_add_u32 s0, s0, 0x40000
	s_addc_u32 s1, s1, 0
	v_lshl_add_u64 v[216:217], v[152:153], 0, s[0:1]
	v_lshl_add_u64 v[218:219], v[154:155], 0, s[0:1]
	v_lshl_add_u64 v[220:221], v[150:151], 0, s[0:1]
	global_load_dwordx4 v[168:171], v[216:217], off
	global_load_dwordx2 v[178:179], v[218:219], off
	global_load_dwordx2 v[180:181], v[220:221], off
	v_permlane32_swap_b32_e32 v0, v16
	v_permlane32_swap_b32_e32 v1, v17
	v_permlane32_swap_b32_e32 v2, v18
	v_permlane32_swap_b32_e32 v3, v19
	v_permlane32_swap_b32_e32 v4, v20
	v_permlane32_swap_b32_e32 v5, v21
	v_permlane32_swap_b32_e32 v6, v22
	v_permlane32_swap_b32_e32 v7, v23
	v_permlane32_swap_b32_e32 v8, v24
	v_permlane32_swap_b32_e32 v9, v25
	v_permlane32_swap_b32_e32 v10, v26
	v_permlane32_swap_b32_e32 v11, v27
	v_permlane32_swap_b32_e32 v12, v28
	v_permlane32_swap_b32_e32 v13, v29
	v_permlane32_swap_b32_e32 v14, v30
	v_permlane32_swap_b32_e32 v15, v31
	v_permlane32_swap_b32_e32 v32, v196
	v_permlane32_swap_b32_e32 v33, v197
	v_permlane32_swap_b32_e32 v34, v198
	v_permlane32_swap_b32_e32 v35, v199
	v_permlane32_swap_b32_e32 v36, v200
	v_permlane32_swap_b32_e32 v37, v201
	v_permlane32_swap_b32_e32 v38, v202
	v_permlane32_swap_b32_e32 v39, v203
	v_permlane32_swap_b32_e32 v40, v204
	v_permlane32_swap_b32_e32 v41, v205
	v_permlane32_swap_b32_e32 v42, v206
	v_permlane32_swap_b32_e32 v43, v207
	v_permlane32_swap_b32_e32 v44, v208
	v_permlane32_swap_b32_e32 v45, v209
	v_permlane32_swap_b32_e32 v46, v210
	v_permlane32_swap_b32_e32 v47, v211
	v_fmac_f32_e32 v0, v160, v188
	v_fmac_f32_e32 v32, v160, v189
	v_fma_f32 v0, -v161, v189, v0
	v_fmac_f32_e32 v32, v161, v188
	v_fmac_f32_e32 v1, v160, v0
	v_fmac_f32_e32 v33, v160, v32
	v_cvt_pk_bf16_f32 v212, v0, v32
	v_fma_f32 v1, -v161, v32, v1
	v_fmac_f32_e32 v33, v161, v0
	ds_write_b32 v185, v212 offset:18432
	v_fmac_f32_e32 v2, v160, v1
	v_fmac_f32_e32 v34, v160, v33
	v_cvt_pk_bf16_f32 v213, v1, v33
	v_fma_f32 v2, -v161, v33, v2
	v_fmac_f32_e32 v34, v161, v1
	ds_write_b32 v185, v213 offset:18704
	v_fmac_f32_e32 v3, v160, v2
	v_fmac_f32_e32 v35, v160, v34
	v_cvt_pk_bf16_f32 v214, v2, v34
	v_fma_f32 v3, -v161, v34, v3
	v_fmac_f32_e32 v35, v161, v2
	ds_write_b32 v185, v214 offset:18976
	v_fmac_f32_e32 v16, v160, v3
	v_fmac_f32_e32 v196, v160, v35
	v_cvt_pk_bf16_f32 v215, v3, v35
	v_fma_f32 v16, -v161, v35, v16
	v_fmac_f32_e32 v196, v161, v3
	ds_write_b32 v185, v215 offset:19248
	v_fmac_f32_e32 v17, v160, v16
	v_fmac_f32_e32 v197, v160, v196
	v_cvt_pk_bf16_f32 v212, v16, v196
	v_fma_f32 v17, -v161, v196, v17
	v_fmac_f32_e32 v197, v161, v16
	ds_write_b32 v185, v212 offset:19520
	v_fmac_f32_e32 v18, v160, v17
	v_fmac_f32_e32 v198, v160, v197
	v_cvt_pk_bf16_f32 v213, v17, v197
	v_fma_f32 v18, -v161, v197, v18
	v_fmac_f32_e32 v198, v161, v17
	ds_write_b32 v185, v213 offset:19792
	v_fmac_f32_e32 v19, v160, v18
	v_fmac_f32_e32 v199, v160, v198
	v_cvt_pk_bf16_f32 v214, v18, v198
	v_fma_f32 v19, -v161, v198, v19
	v_fmac_f32_e32 v199, v161, v18
	ds_write_b32 v185, v214 offset:20064
	v_fmac_f32_e32 v4, v160, v19
	v_fmac_f32_e32 v36, v160, v199
	v_cvt_pk_bf16_f32 v215, v19, v199
	v_fma_f32 v4, -v161, v199, v4
	v_fmac_f32_e32 v36, v161, v19
	ds_write_b32 v185, v215 offset:20336
	v_fmac_f32_e32 v5, v160, v4
	v_fmac_f32_e32 v37, v160, v36
	v_cvt_pk_bf16_f32 v212, v4, v36
	v_fma_f32 v5, -v161, v36, v5
	v_fmac_f32_e32 v37, v161, v4
	ds_write_b32 v185, v212 offset:20608
	v_fmac_f32_e32 v6, v160, v5
	v_fmac_f32_e32 v38, v160, v37
	v_cvt_pk_bf16_f32 v213, v5, v37
	v_fma_f32 v6, -v161, v37, v6
	v_fmac_f32_e32 v38, v161, v5
	ds_write_b32 v185, v213 offset:20880
	v_fmac_f32_e32 v7, v160, v6
	v_fmac_f32_e32 v39, v160, v38
	v_cvt_pk_bf16_f32 v214, v6, v38
	v_fma_f32 v7, -v161, v38, v7
	v_fmac_f32_e32 v39, v161, v6
	ds_write_b32 v185, v214 offset:21152
	v_fmac_f32_e32 v20, v160, v7
	v_fmac_f32_e32 v200, v160, v39
	v_cvt_pk_bf16_f32 v215, v7, v39
	v_fma_f32 v20, -v161, v39, v20
	v_fmac_f32_e32 v200, v161, v7
	ds_write_b32 v185, v215 offset:21424
	v_fmac_f32_e32 v21, v160, v20
	v_fmac_f32_e32 v201, v160, v200
	v_cvt_pk_bf16_f32 v212, v20, v200
	v_fma_f32 v21, -v161, v200, v21
	v_fmac_f32_e32 v201, v161, v20
	ds_write_b32 v185, v212 offset:21696
	v_fmac_f32_e32 v22, v160, v21
	v_fmac_f32_e32 v202, v160, v201
	v_cvt_pk_bf16_f32 v213, v21, v201
	v_fma_f32 v22, -v161, v201, v22
	v_fmac_f32_e32 v202, v161, v21
	ds_write_b32 v185, v213 offset:21968
	v_fmac_f32_e32 v23, v160, v22
	v_fmac_f32_e32 v203, v160, v202
	v_cvt_pk_bf16_f32 v214, v22, v202
	v_fma_f32 v23, -v161, v202, v23
	v_fmac_f32_e32 v203, v161, v22
	ds_write_b32 v185, v214 offset:22240
	v_fmac_f32_e32 v8, v160, v23
	v_fmac_f32_e32 v40, v160, v203
	v_cvt_pk_bf16_f32 v215, v23, v203
	v_fma_f32 v8, -v161, v203, v8
	v_fmac_f32_e32 v40, v161, v23
	ds_write_b32 v185, v215 offset:22512
	v_fmac_f32_e32 v9, v160, v8
	v_fmac_f32_e32 v41, v160, v40
	v_cvt_pk_bf16_f32 v212, v8, v40
	v_fma_f32 v9, -v161, v40, v9
	v_fmac_f32_e32 v41, v161, v8
	ds_write_b32 v185, v212 offset:22784
	v_fmac_f32_e32 v10, v160, v9
	v_fmac_f32_e32 v42, v160, v41
	v_cvt_pk_bf16_f32 v213, v9, v41
	v_fma_f32 v10, -v161, v41, v10
	v_fmac_f32_e32 v42, v161, v9
	ds_write_b32 v185, v213 offset:23056
	v_fmac_f32_e32 v11, v160, v10
	v_fmac_f32_e32 v43, v160, v42
	v_cvt_pk_bf16_f32 v214, v10, v42
	v_fma_f32 v11, -v161, v42, v11
	v_fmac_f32_e32 v43, v161, v10
	ds_write_b32 v185, v214 offset:23328
	v_fmac_f32_e32 v24, v160, v11
	v_fmac_f32_e32 v204, v160, v43
	v_cvt_pk_bf16_f32 v215, v11, v43
	v_fma_f32 v24, -v161, v43, v24
	v_fmac_f32_e32 v204, v161, v11
	ds_write_b32 v185, v215 offset:23600
	v_fmac_f32_e32 v25, v160, v24
	v_fmac_f32_e32 v205, v160, v204
	v_cvt_pk_bf16_f32 v212, v24, v204
	v_fma_f32 v25, -v161, v204, v25
	v_fmac_f32_e32 v205, v161, v24
	ds_write_b32 v185, v212 offset:23872
	v_fmac_f32_e32 v26, v160, v25
	v_fmac_f32_e32 v206, v160, v205
	v_cvt_pk_bf16_f32 v213, v25, v205
	v_fma_f32 v26, -v161, v205, v26
	v_fmac_f32_e32 v206, v161, v25
	ds_write_b32 v185, v213 offset:24144
	v_fmac_f32_e32 v27, v160, v26
	v_fmac_f32_e32 v207, v160, v206
	v_cvt_pk_bf16_f32 v214, v26, v206
	v_fma_f32 v27, -v161, v206, v27
	v_fmac_f32_e32 v207, v161, v26
	ds_write_b32 v185, v214 offset:24416
	v_fmac_f32_e32 v12, v160, v27
	v_fmac_f32_e32 v44, v160, v207
	v_cvt_pk_bf16_f32 v215, v27, v207
	v_fma_f32 v12, -v161, v207, v12
	v_fmac_f32_e32 v44, v161, v27
	ds_write_b32 v185, v215 offset:24688
	v_fmac_f32_e32 v13, v160, v12
	v_fmac_f32_e32 v45, v160, v44
	v_cvt_pk_bf16_f32 v212, v12, v44
	v_fma_f32 v13, -v161, v44, v13
	v_fmac_f32_e32 v45, v161, v12
	ds_write_b32 v185, v212 offset:24960
	v_fmac_f32_e32 v14, v160, v13
	v_fmac_f32_e32 v46, v160, v45
	v_cvt_pk_bf16_f32 v213, v13, v45
	v_fma_f32 v14, -v161, v45, v14
	v_fmac_f32_e32 v46, v161, v13
	ds_write_b32 v185, v213 offset:25232
	v_fmac_f32_e32 v15, v160, v14
	v_fmac_f32_e32 v47, v160, v46
	v_cvt_pk_bf16_f32 v214, v14, v46
	v_fma_f32 v15, -v161, v46, v15
	v_fmac_f32_e32 v47, v161, v14
	ds_write_b32 v185, v214 offset:25504
	v_fmac_f32_e32 v28, v160, v15
	v_fmac_f32_e32 v208, v160, v47
	v_cvt_pk_bf16_f32 v215, v15, v47
	v_fma_f32 v28, -v161, v47, v28
	v_fmac_f32_e32 v208, v161, v15
	ds_write_b32 v185, v215 offset:25776
	v_fmac_f32_e32 v29, v160, v28
	v_fmac_f32_e32 v209, v160, v208
	v_cvt_pk_bf16_f32 v212, v28, v208
	v_fma_f32 v29, -v161, v208, v29
	v_fmac_f32_e32 v209, v161, v28
	ds_write_b32 v185, v212 offset:26048
	v_fmac_f32_e32 v30, v160, v29
	v_fmac_f32_e32 v210, v160, v209
	v_cvt_pk_bf16_f32 v213, v29, v209
	v_fma_f32 v30, -v161, v209, v30
	v_fmac_f32_e32 v210, v161, v29
	ds_write_b32 v185, v213 offset:26320
	v_fmac_f32_e32 v31, v160, v30
	v_fmac_f32_e32 v211, v160, v210
	v_cvt_pk_bf16_f32 v214, v30, v210
	v_fma_f32 v31, -v161, v210, v31
	v_fmac_f32_e32 v211, v161, v30
	ds_write_b32 v185, v214 offset:26592
	v_mov_b32_e32 v188, v31
	v_mov_b32_e32 v189, v211
	v_cvt_pk_bf16_f32 v215, v31, v211
	ds_write_b32 v185, v215 offset:26864
	s_waitcnt lgkmcnt(0)
	ds_read_b128 v[32:35], v186 offset:18432
	ds_read_b128 v[36:39], v186 offset:18464
	ds_read_b128 v[40:43], v186 offset:18496
	ds_read_b128 v[44:47], v186 offset:18528
	ds_read_b128 v[196:199], v186 offset:18560
	ds_read_b128 v[200:203], v186 offset:18592
	ds_read_b128 v[204:207], v186 offset:18624
	ds_read_b128 v[208:211], v186 offset:18656
	s_waitcnt lgkmcnt(7)
	v_mfma_f32_32x32x16_bf16 v[234:249], v[64:67], v[32:35], 0
	v_fmac_f32_e32 v48, v100, v228
	v_fmac_f32_e32 v49, v101, v229
	v_fmac_f32_e32 v50, v102, v230
	v_fmac_f32_e32 v51, v103, v231
	v_fmac_f32_e32 v52, v80, v232
	v_fmac_f32_e32 v53, v81, v233
	v_fmac_f32_e32 v54, v82, v251
	v_fmac_f32_e32 v55, v83, v252
	v_mul_f32_e32 v56, v48, v48
	s_waitcnt lgkmcnt(6)
	v_mfma_f32_32x32x16_bf16 v[234:249], v[68:71], v[36:39], v[234:249]
	v_mul_f32_e32 v57, v49, v49
	v_mul_f32_e32 v58, v50, v50
	v_mul_f32_e32 v59, v51, v51
	v_mul_f32_e32 v60, v52, v52
	v_mul_f32_e32 v61, v53, v53
	v_mul_f32_e32 v62, v54, v54
	v_mul_f32_e32 v63, v55, v55
	v_fmaak_f32 v56, v56, v184, 0xc0135761
	v_fmaak_f32 v57, v57, v184, 0xc0135761
	s_waitcnt lgkmcnt(5)
	v_mfma_f32_32x32x16_bf16 v[234:249], v[72:75], v[40:43], v[234:249]
	v_fmaak_f32 v58, v58, v184, 0xc0135761
	v_fmaak_f32 v59, v59, v184, 0xc0135761
	v_fmaak_f32 v60, v60, v184, 0xc0135761
	v_fmaak_f32 v61, v61, v184, 0xc0135761
	v_fmaak_f32 v62, v62, v184, 0xc0135761
	v_fmaak_f32 v63, v63, v184, 0xc0135761
	v_mul_f32_e32 v56, v48, v56
	v_mul_f32_e32 v57, v49, v57
	v_mul_f32_e32 v58, v50, v58
	s_waitcnt lgkmcnt(4)
	v_mfma_f32_32x32x16_bf16 v[234:249], v[76:79], v[44:47], v[234:249]
	v_mul_f32_e32 v59, v51, v59
	v_mul_f32_e32 v60, v52, v60
	v_mul_f32_e32 v61, v53, v61
	v_mul_f32_e32 v62, v54, v62
	v_mul_f32_e32 v63, v55, v63
	v_exp_f32_e32 v56, v56
	v_exp_f32_e32 v57, v57
	v_exp_f32_e32 v58, v58
	v_exp_f32_e32 v59, v59
	s_waitcnt lgkmcnt(3)
	v_mfma_f32_32x32x16_bf16 v[234:249], v[84:87], v[196:199], v[234:249]
	v_exp_f32_e32 v60, v60
	v_exp_f32_e32 v61, v61
	v_exp_f32_e32 v62, v62
	v_exp_f32_e32 v63, v63
	v_add_f32_e32 v56, 1.0, v56
	v_add_f32_e32 v57, 1.0, v57
	v_add_f32_e32 v58, 1.0, v58
	v_add_f32_e32 v59, 1.0, v59
	s_waitcnt lgkmcnt(2)
	v_mfma_f32_32x32x16_bf16 v[234:249], v[88:91], v[200:203], v[234:249]
	v_add_f32_e32 v60, 1.0, v60
	v_add_f32_e32 v61, 1.0, v61
	v_add_f32_e32 v62, 1.0, v62
	v_add_f32_e32 v63, 1.0, v63
	v_rcp_f32_e32 v56, v56
	v_rcp_f32_e32 v57, v57
	v_rcp_f32_e32 v58, v58
	v_rcp_f32_e32 v59, v59
	s_waitcnt lgkmcnt(1)
	v_mfma_f32_32x32x16_bf16 v[234:249], v[96:99], v[204:207], v[234:249]
	v_rcp_f32_e32 v60, v60
	v_rcp_f32_e32 v61, v61
	v_rcp_f32_e32 v62, v62
	v_rcp_f32_e32 v63, v63
	v_mul_f32_e32 v48, v48, v56
	v_mul_f32_e32 v49, v49, v57
	v_mul_f32_e32 v50, v50, v58
	v_mul_f32_e32 v51, v51, v59
	s_waitcnt lgkmcnt(0)
	v_mfma_f32_32x32x16_bf16 v[234:249], v[108:111], v[208:211], v[234:249]
	v_mul_f32_e32 v52, v52, v60
	v_mul_f32_e32 v53, v53, v61
	v_mul_f32_e32 v54, v54, v62
	v_mul_f32_e32 v55, v55, v63
	v_cvt_pk_bf16_f32 v56, v48, v49
	v_cvt_pk_bf16_f32 v57, v50, v51
	v_cvt_pk_bf16_f32 v58, v52, v53
	v_cvt_pk_bf16_f32 v59, v54, v55
	global_store_dwordx2 v253, v[56:57], s[90:91]
	global_store_dwordx2 v254, v[58:59], s[90:91]
	s_add_i32 s2, s2, 32
	v_add_u32_e32 v187, 4, v187
	s_cmp_eq_u32 s0, 0x1000000
	s_cbranch_scc0 .Lscan_tile
	s_nop 11
	v_fmac_f32_e32 v234, v100, v162
	v_fmac_f32_e32 v235, v101, v163
	v_fmac_f32_e32 v236, v102, v164
	v_fmac_f32_e32 v237, v103, v165
	v_fmac_f32_e32 v238, v80, v166
	v_fmac_f32_e32 v239, v81, v167
	v_fmac_f32_e32 v240, v82, v192
	v_fmac_f32_e32 v241, v83, v193
	v_mul_f32_e32 v242, v234, v234
	v_mul_f32_e32 v243, v235, v235
	v_mul_f32_e32 v244, v236, v236
	v_mul_f32_e32 v245, v237, v237
	v_mul_f32_e32 v246, v238, v238
	v_mul_f32_e32 v247, v239, v239
	v_mul_f32_e32 v248, v240, v240
	v_mul_f32_e32 v249, v241, v241
	v_fmaak_f32 v242, v242, v184, 0xc0135761
	v_fmaak_f32 v243, v243, v184, 0xc0135761
	v_fmaak_f32 v244, v244, v184, 0xc0135761
	v_fmaak_f32 v245, v245, v184, 0xc0135761
	v_fmaak_f32 v246, v246, v184, 0xc0135761
	v_fmaak_f32 v247, v247, v184, 0xc0135761
	v_fmaak_f32 v248, v248, v184, 0xc0135761
	v_fmaak_f32 v249, v249, v184, 0xc0135761
	v_mul_f32_e32 v242, v234, v242
	v_mul_f32_e32 v243, v235, v243
	v_mul_f32_e32 v244, v236, v244
	v_mul_f32_e32 v245, v237, v245
	v_mul_f32_e32 v246, v238, v246
	v_mul_f32_e32 v247, v239, v247
	v_mul_f32_e32 v248, v240, v248
	v_mul_f32_e32 v249, v241, v249
	v_exp_f32_e32 v242, v242
	v_exp_f32_e32 v243, v243
	v_exp_f32_e32 v244, v244
	v_exp_f32_e32 v245, v245
	v_exp_f32_e32 v246, v246
	v_exp_f32_e32 v247, v247
	v_exp_f32_e32 v248, v248
	v_exp_f32_e32 v249, v249
	v_add_f32_e32 v242, 1.0, v242
	v_add_f32_e32 v243, 1.0, v243
	v_add_f32_e32 v244, 1.0, v244
	v_add_f32_e32 v245, 1.0, v245
	v_add_f32_e32 v246, 1.0, v246
	v_add_f32_e32 v247, 1.0, v247
	v_add_f32_e32 v248, 1.0, v248
	v_add_f32_e32 v249, 1.0, v249
	v_rcp_f32_e32 v242, v242
	v_rcp_f32_e32 v243, v243
	v_rcp_f32_e32 v244, v244
	v_rcp_f32_e32 v245, v245
	v_rcp_f32_e32 v246, v246
	v_rcp_f32_e32 v247, v247
	v_rcp_f32_e32 v248, v248
	v_rcp_f32_e32 v249, v249
	v_mul_f32_e32 v234, v234, v242
	v_mul_f32_e32 v235, v235, v243
	v_mul_f32_e32 v236, v236, v244
	v_mul_f32_e32 v237, v237, v245
	v_mul_f32_e32 v238, v238, v246
	v_mul_f32_e32 v239, v239, v247
	v_mul_f32_e32 v240, v240, v248
	v_mul_f32_e32 v241, v241, v249
	v_cvt_pk_bf16_f32 v242, v234, v235
	v_cvt_pk_bf16_f32 v243, v236, v237
	v_cvt_pk_bf16_f32 v244, v238, v239
	v_cvt_pk_bf16_f32 v245, v240, v241
	global_store_dwordx2 v190, v[242:243], s[90:91]
	global_store_dwordx2 v191, v[244:245], s[90:91]
	s_add_i32 s6, s6, s7
	s_add_i32 s10, s10, s11
	s_add_i32 s12, s12, s7
	s_cmpk_gt_i32 s6, 0x3ff
	s_cbranch_scc0 .LBB0_563
